# v10 + phase C stores P1 tiles (attention q,k,v) with plain stores instead of nt so they stay cached for D1; P2/P3 keep nt
# speedup vs baseline: 1.0106x; 1.0106x over previous
.LBB0_188:
	s_cmp_lt_u32 s36, 12
	s_cbranch_scc1 .Lc_epi_plain
	s_lshl_b32 s11, s36, 8
	s_mul_hi_i32 s13, s11, 0x2aaaaaab
	s_lshr_b32 s18, s13, 31
	s_lshr_b32 s13, s13, 9
	s_add_i32 s13, s13, s18
	s_mulk_i32 s13, 0xc00
	s_sub_i32 s18, s11, s13
	s_add_i32 s11, s36, 11
	s_add_i32 s13, s36, -12
	s_cmp_lt_u32 s13, 12
	s_cselect_b32 s13, s34, 0x8800000
	s_cmp_gt_u32 s11, 22
	s_cselect_b32 s11, s13, 0xe800000
	s_add_u32 s11, s58, s11
	s_addc_u32 s13, s59, 0
	s_ashr_i32 s19, s18, 31
	s_lshl_b64 s[18:19], s[18:19], 1
	s_add_u32 s18, s11, s18
	v_lshl_add_u32 v147, s33, 8, v142
	s_addc_u32 s19, s13, s19
	v_mov_b64_e32 v[148:149], s[18:19]
	v_cvt_pk_bf16_f32 v68, v68, v69
	v_cvt_pk_bf16_f32 v69, v70, v71
	v_cvt_pk_bf16_f32 v70, v64, v65
	v_add_u32_e32 v64, 0x80, v147
	v_mad_i64_i32 v[150:151], s[18:19], v147, s35, v[148:149]
	v_mad_i64_i32 v[64:65], s[18:19], v64, s35, v[148:149]
	v_cvt_pk_bf16_f32 v124, v124, v125
	v_cvt_pk_bf16_f32 v125, v126, v127
	v_cvt_pk_bf16_f32 v126, v120, v121
	v_lshl_add_u64 v[120:121], v[150:151], 0, v[132:133]
	v_cvt_pk_bf16_f32 v108, v108, v109
	v_cvt_pk_bf16_f32 v109, v110, v111
	v_cvt_pk_bf16_f32 v110, v104, v105
	v_cvt_pk_bf16_f32 v111, v106, v107
	v_or_b32_e32 v104, 16, v147
	v_cvt_pk_bf16_f32 v60, v60, v61
	v_cvt_pk_bf16_f32 v61, v62, v63
	v_cvt_pk_bf16_f32 v62, v56, v57
	v_lshl_add_u64 v[56:57], v[64:65], 0, v[132:133]
	v_cvt_pk_bf16_f32 v44, v44, v45
	v_cvt_pk_bf16_f32 v45, v46, v47
	v_cvt_pk_bf16_f32 v46, v40, v41
	v_cvt_pk_bf16_f32 v47, v42, v43
	v_add_u32_e32 v40, 0x90, v147
	global_store_dwordx4 v[120:121], v[108:111], off offset:256 nt
	global_store_dwordx4 v[56:57], v[44:47], off offset:256 nt
	v_cvt_pk_bf16_f32 v92, v92, v93
	v_mad_i64_i32 v[108:109], s[18:19], v104, s35, v[148:149]
	v_mad_i64_i32 v[44:45], s[18:19], v40, s35, v[148:149]
	v_lshl_add_u64 v[108:109], v[108:109], 0, v[132:133]
	v_cvt_pk_bf16_f32 v93, v94, v95
	v_cvt_pk_bf16_f32 v94, v88, v89
	v_cvt_pk_bf16_f32 v95, v90, v91
	v_or_b32_e32 v88, 32, v147
	v_lshl_add_u64 v[44:45], v[44:45], 0, v[132:133]
	v_cvt_pk_bf16_f32 v28, v28, v29
	v_cvt_pk_bf16_f32 v29, v30, v31
	v_cvt_pk_bf16_f32 v30, v24, v25
	v_cvt_pk_bf16_f32 v31, v26, v27
	v_add_u32_e32 v24, 0xa0, v147
	global_store_dwordx4 v[108:109], v[92:95], off offset:256 nt
	global_store_dwordx4 v[44:45], v[28:31], off offset:256 nt
	v_cvt_pk_bf16_f32 v76, v76, v77
	v_mad_i64_i32 v[92:93], s[18:19], v88, s35, v[148:149]
	v_mad_i64_i32 v[28:29], s[18:19], v24, s35, v[148:149]
	v_lshl_add_u64 v[92:93], v[92:93], 0, v[132:133]
	v_cvt_pk_bf16_f32 v77, v78, v79
	v_cvt_pk_bf16_f32 v78, v72, v73
	v_cvt_pk_bf16_f32 v79, v74, v75
	v_or_b32_e32 v72, 48, v147
	v_lshl_add_u64 v[28:29], v[28:29], 0, v[132:133]
	v_cvt_pk_bf16_f32 v12, v12, v13
	v_cvt_pk_bf16_f32 v13, v14, v15
	v_cvt_pk_bf16_f32 v14, v8, v9
	v_cvt_pk_bf16_f32 v15, v10, v11
	v_add_u32_e32 v8, 0xb0, v147
	global_store_dwordx4 v[92:93], v[76:79], off offset:256 nt
	global_store_dwordx4 v[28:29], v[12:15], off offset:256 nt
	v_cvt_pk_bf16_f32 v127, v122, v123
	v_mad_i64_i32 v[76:77], s[18:19], v72, s35, v[148:149]
	v_mad_i64_i32 v[12:13], s[18:19], v8, s35, v[148:149]
	v_cvt_pk_bf16_f32 v104, v116, v117
	v_cvt_pk_bf16_f32 v105, v118, v119
	v_cvt_pk_bf16_f32 v106, v112, v113
	v_cvt_pk_bf16_f32 v107, v114, v115
	v_cvt_pk_bf16_f32 v88, v100, v101
	v_cvt_pk_bf16_f32 v89, v102, v103
	v_cvt_pk_bf16_f32 v90, v96, v97
	v_cvt_pk_bf16_f32 v91, v98, v99
	v_cvt_pk_bf16_f32 v72, v84, v85
	v_cvt_pk_bf16_f32 v73, v86, v87
	v_cvt_pk_bf16_f32 v74, v80, v81
	v_cvt_pk_bf16_f32 v75, v82, v83
	v_lshl_add_u64 v[76:77], v[76:77], 0, v[132:133]
	v_cvt_pk_bf16_f32 v71, v66, v67
	v_cvt_pk_bf16_f32 v63, v58, v59
	v_cvt_pk_bf16_f32 v40, v52, v53
	v_cvt_pk_bf16_f32 v41, v54, v55
	v_cvt_pk_bf16_f32 v42, v48, v49
	v_cvt_pk_bf16_f32 v43, v50, v51
	v_cvt_pk_bf16_f32 v24, v36, v37
	v_cvt_pk_bf16_f32 v25, v38, v39
	v_cvt_pk_bf16_f32 v26, v32, v33
	v_cvt_pk_bf16_f32 v27, v34, v35
	v_cvt_pk_bf16_f32 v8, v20, v21
	v_cvt_pk_bf16_f32 v9, v22, v23
	v_cvt_pk_bf16_f32 v10, v16, v17
	v_cvt_pk_bf16_f32 v11, v18, v19
	v_lshl_add_u64 v[12:13], v[12:13], 0, v[132:133]
	v_cvt_pk_bf16_f32 v4, v4, v5
	v_cvt_pk_bf16_f32 v5, v6, v7
	v_cvt_pk_bf16_f32 v6, v0, v1
	v_cvt_pk_bf16_f32 v7, v2, v3
	s_andn2_b64 vcc, exec, s[0:1]
	s_mov_b64 s[0:1], -1
	global_store_dwordx4 v[120:121], v[124:127], off nt
	global_store_dwordx4 v[108:109], v[104:107], off nt
	global_store_dwordx4 v[92:93], v[88:91], off nt
	global_store_dwordx4 v[76:77], v[72:75], off nt
	global_store_dwordx4 v[76:77], v[68:71], off offset:256 nt
	global_store_dwordx4 v[56:57], v[60:63], off nt
	global_store_dwordx4 v[44:45], v[40:43], off nt
	global_store_dwordx4 v[28:29], v[24:27], off nt
	global_store_dwordx4 v[12:13], v[8:11], off nt
	global_store_dwordx4 v[12:13], v[4:7], off offset:256 nt
	s_branch .Lc_epi_join
.Lc_epi_plain:
	s_lshl_b32 s11, s36, 8
	s_mul_hi_i32 s13, s11, 0x2aaaaaab
	s_lshr_b32 s18, s13, 31
	s_lshr_b32 s13, s13, 9
	s_add_i32 s13, s13, s18
	s_mulk_i32 s13, 0xc00
	s_sub_i32 s18, s11, s13
	s_add_i32 s11, s36, 11
	s_add_i32 s13, s36, -12
	s_cmp_lt_u32 s13, 12
	s_cselect_b32 s13, s34, 0x8800000
	s_cmp_gt_u32 s11, 22
	s_cselect_b32 s11, s13, 0xe800000
	s_add_u32 s11, s58, s11
	s_addc_u32 s13, s59, 0
	s_ashr_i32 s19, s18, 31
	s_lshl_b64 s[18:19], s[18:19], 1
	s_add_u32 s18, s11, s18
	v_lshl_add_u32 v147, s33, 8, v142
	s_addc_u32 s19, s13, s19
	v_mov_b64_e32 v[148:149], s[18:19]
	v_cvt_pk_bf16_f32 v68, v68, v69
	v_cvt_pk_bf16_f32 v69, v70, v71
	v_cvt_pk_bf16_f32 v70, v64, v65
	v_add_u32_e32 v64, 0x80, v147
	v_mad_i64_i32 v[150:151], s[18:19], v147, s35, v[148:149]
	v_mad_i64_i32 v[64:65], s[18:19], v64, s35, v[148:149]
	v_cvt_pk_bf16_f32 v124, v124, v125
	v_cvt_pk_bf16_f32 v125, v126, v127
	v_cvt_pk_bf16_f32 v126, v120, v121
	v_lshl_add_u64 v[120:121], v[150:151], 0, v[132:133]
	v_cvt_pk_bf16_f32 v108, v108, v109
	v_cvt_pk_bf16_f32 v109, v110, v111
	v_cvt_pk_bf16_f32 v110, v104, v105
	v_cvt_pk_bf16_f32 v111, v106, v107
	v_or_b32_e32 v104, 16, v147
	v_cvt_pk_bf16_f32 v60, v60, v61
	v_cvt_pk_bf16_f32 v61, v62, v63
	v_cvt_pk_bf16_f32 v62, v56, v57
	v_lshl_add_u64 v[56:57], v[64:65], 0, v[132:133]
	v_cvt_pk_bf16_f32 v44, v44, v45
	v_cvt_pk_bf16_f32 v45, v46, v47
	v_cvt_pk_bf16_f32 v46, v40, v41
	v_cvt_pk_bf16_f32 v47, v42, v43
	v_add_u32_e32 v40, 0x90, v147
	global_store_dwordx4 v[120:121], v[108:111], off offset:256
	global_store_dwordx4 v[56:57], v[44:47], off offset:256
	v_cvt_pk_bf16_f32 v92, v92, v93
	v_mad_i64_i32 v[108:109], s[18:19], v104, s35, v[148:149]
	v_mad_i64_i32 v[44:45], s[18:19], v40, s35, v[148:149]
	v_lshl_add_u64 v[108:109], v[108:109], 0, v[132:133]
	v_cvt_pk_bf16_f32 v93, v94, v95
	v_cvt_pk_bf16_f32 v94, v88, v89
	v_cvt_pk_bf16_f32 v95, v90, v91
	v_or_b32_e32 v88, 32, v147
	v_lshl_add_u64 v[44:45], v[44:45], 0, v[132:133]
	v_cvt_pk_bf16_f32 v28, v28, v29
	v_cvt_pk_bf16_f32 v29, v30, v31
	v_cvt_pk_bf16_f32 v30, v24, v25
	v_cvt_pk_bf16_f32 v31, v26, v27
	v_add_u32_e32 v24, 0xa0, v147
	global_store_dwordx4 v[108:109], v[92:95], off offset:256
	global_store_dwordx4 v[44:45], v[28:31], off offset:256
	v_cvt_pk_bf16_f32 v76, v76, v77
	v_mad_i64_i32 v[92:93], s[18:19], v88, s35, v[148:149]
	v_mad_i64_i32 v[28:29], s[18:19], v24, s35, v[148:149]
	v_lshl_add_u64 v[92:93], v[92:93], 0, v[132:133]
	v_cvt_pk_bf16_f32 v77, v78, v79
	v_cvt_pk_bf16_f32 v78, v72, v73
	v_cvt_pk_bf16_f32 v79, v74, v75
	v_or_b32_e32 v72, 48, v147
	v_lshl_add_u64 v[28:29], v[28:29], 0, v[132:133]
	v_cvt_pk_bf16_f32 v12, v12, v13
	v_cvt_pk_bf16_f32 v13, v14, v15
	v_cvt_pk_bf16_f32 v14, v8, v9
	v_cvt_pk_bf16_f32 v15, v10, v11
	v_add_u32_e32 v8, 0xb0, v147
	global_store_dwordx4 v[92:93], v[76:79], off offset:256
	global_store_dwordx4 v[28:29], v[12:15], off offset:256
	v_cvt_pk_bf16_f32 v127, v122, v123
	v_mad_i64_i32 v[76:77], s[18:19], v72, s35, v[148:149]
	v_mad_i64_i32 v[12:13], s[18:19], v8, s35, v[148:149]
	v_cvt_pk_bf16_f32 v104, v116, v117
	v_cvt_pk_bf16_f32 v105, v118, v119
	v_cvt_pk_bf16_f32 v106, v112, v113
	v_cvt_pk_bf16_f32 v107, v114, v115
	v_cvt_pk_bf16_f32 v88, v100, v101
	v_cvt_pk_bf16_f32 v89, v102, v103
	v_cvt_pk_bf16_f32 v90, v96, v97
	v_cvt_pk_bf16_f32 v91, v98, v99
	v_cvt_pk_bf16_f32 v72, v84, v85
	v_cvt_pk_bf16_f32 v73, v86, v87
	v_cvt_pk_bf16_f32 v74, v80, v81
	v_cvt_pk_bf16_f32 v75, v82, v83
	v_lshl_add_u64 v[76:77], v[76:77], 0, v[132:133]
	v_cvt_pk_bf16_f32 v71, v66, v67
	v_cvt_pk_bf16_f32 v63, v58, v59
	v_cvt_pk_bf16_f32 v40, v52, v53
	v_cvt_pk_bf16_f32 v41, v54, v55
	v_cvt_pk_bf16_f32 v42, v48, v49
	v_cvt_pk_bf16_f32 v43, v50, v51
	v_cvt_pk_bf16_f32 v24, v36, v37
	v_cvt_pk_bf16_f32 v25, v38, v39
	v_cvt_pk_bf16_f32 v26, v32, v33
	v_cvt_pk_bf16_f32 v27, v34, v35
	v_cvt_pk_bf16_f32 v8, v20, v21
	v_cvt_pk_bf16_f32 v9, v22, v23
	v_cvt_pk_bf16_f32 v10, v16, v17
	v_cvt_pk_bf16_f32 v11, v18, v19
	v_lshl_add_u64 v[12:13], v[12:13], 0, v[132:133]
	v_cvt_pk_bf16_f32 v4, v4, v5
	v_cvt_pk_bf16_f32 v5, v6, v7
	v_cvt_pk_bf16_f32 v6, v0, v1
	v_cvt_pk_bf16_f32 v7, v2, v3
	s_andn2_b64 vcc, exec, s[0:1]
	s_mov_b64 s[0:1], -1
	global_store_dwordx4 v[120:121], v[124:127], off
	global_store_dwordx4 v[108:109], v[104:107], off
	global_store_dwordx4 v[92:93], v[88:91], off
	global_store_dwordx4 v[76:77], v[72:75], off
	global_store_dwordx4 v[76:77], v[68:71], off offset:256
	global_store_dwordx4 v[56:57], v[60:63], off
	global_store_dwordx4 v[44:45], v[40:43], off
	global_store_dwordx4 v[28:29], v[24:27], off
	global_store_dwordx4 v[12:13], v[8:11], off
	global_store_dwordx4 v[12:13], v[4:7], off offset:256
.Lc_epi_join:
	s_cbranch_vccnz .LBB0_181
	s_andn2_b64 vcc, exec, s[4:5]
	s_cbranch_vccnz .LBB0_180
	s_barrier
	s_branch .LBB0_180
